# st6 + P3 group-norm gains requested before the P2->P3 per-batch sync (copied into place after it)
# baseline (speedup 1.0000x reference)
.LBB0_230:
	s_cmp_eq_u32 s58, 0x100
	s_cbranch_scc0 .Lb3_generic
	s_waitcnt vmcnt(0)
	s_barrier
	v_lshlrev_b32_e32 v168, 5, v0
	v_readlane_b32 s6, v244, 4
	v_readlane_b32 s7, v244, 5
	v_and_b32_e32 v168, 0x7e0, v168
	s_nop 4
	global_load_dwordx4 v[160:163], v168, s[6:7] offset:16
	global_load_dwordx4 v[164:167], v168, s[6:7]
	s_mov_b64 s[0:1], exec
	v_readlane_b32 s4, v244, 8
	v_readlane_b32 s5, v244, 9
	s_and_b64 s[4:5], s[0:1], s[4:5]
	s_mov_b64 exec, s[4:5]
	s_cbranch_execz .LBB0_282
	s_and_b32 s2, s57, 7
	s_lshl_b32 s2, s2, 8
	s_add_u32 s2, s2, 0x3600
	v_mov_b32_e32 v2, s2
	v_mov_b32_e32 v3, 1
	s_mov_b32 s3, 0
	global_atomic_add v2, v3, s[52:53]

.LBB0_282:
	s_or_b64 exec, exec, s[0:1]
	v_readlane_b32 s0, v244, 28
	v_readlane_b32 s1, v244, 29
	v_mov_b32_e32 v10, v0
	s_andn2_b64 vcc, exec, s[0:1]
	s_waitcnt lgkmcnt(0)
	s_barrier
	s_cbranch_vccnz .LBB0_295
	v_lshlrev_b32_e32 v2, 5, v10
	v_readlane_b32 s0, v244, 0
	v_and_b32_e32 v12, 0x7e0, v2
	v_readlane_b32 s4, v244, 4
	v_readlane_b32 s5, v244, 5
	s_nop 4
	s_cmp_eq_u32 s58, 0x100
	s_cbranch_scc0 .Lp3_gn_ld
	s_waitcnt vmcnt(0)
	v_mov_b64_e32 v[2:3], v[160:161]
	v_mov_b64_e32 v[4:5], v[162:163]
	v_mov_b64_e32 v[6:7], v[164:165]
	v_mov_b64_e32 v[8:9], v[166:167]
	s_branch .Lp3_gn_done
.Lp3_gn_ld:
	global_load_dwordx4 v[2:5], v12, s[4:5] offset:16
	global_load_dwordx4 v[6:9], v12, s[4:5]
.Lp3_gn_done:
	v_ashrrev_i32_e32 v13, 2, v10
	v_mbcnt_hi_u32_b32 v14, -1, v1
	v_and_b32_e32 v1, 63, v10
	v_and_b32_e32 v20, -16, v13
	v_and_b32_e32 v13, 64, v14
	v_readlane_b32 s1, v244, 1
	v_ashrrev_i32_e32 v11, 31, v10
	v_xor_b32_e32 v15, 1, v14
	v_lshlrev_b32_e32 v18, 4, v1
	v_add_u32_e32 v1, 0, v12
	v_add_u32_e32 v12, 64, v13
	v_lshl_add_u32 v146, v10, 2, 0
	s_mov_b64 s[0:1], 0x15de7800
	s_mov_b64 s[4:5], 0x15de0800
	v_xor_b32_e32 v16, 2, v14
	v_lshl_add_u64 v[10:11], v[10:11], 2, s[62:63]
	v_cmp_lt_i32_e32 vcc, v15, v12
	v_xor_b32_e32 v17, 4, v14
	v_lshl_add_u64 v[22:23], v[10:11], 0, s[0:1]
	v_lshl_add_u64 v[24:25], v[10:11], 0, s[4:5]
	v_cndmask_b32_e32 v10, v14, v15, vcc
	v_cmp_lt_i32_e32 vcc, v16, v12
	v_xor_b32_e32 v26, 8, v14
	v_xor_b32_e32 v27, 16, v14
	v_cndmask_b32_e32 v11, v14, v16, vcc
	v_cmp_lt_i32_e32 vcc, v17, v12
	v_xor_b32_e32 v28, 32, v14
	v_readlane_b32 s3, v244, 3
	v_cndmask_b32_e32 v13, v14, v17, vcc
	v_cmp_lt_i32_e32 vcc, v26, v12
	s_mov_b32 s3, 0
	v_mov_b32_e32 v19, 0
	v_cndmask_b32_e32 v15, v14, v26, vcc
	v_cmp_lt_i32_e32 vcc, v27, v12
	s_mov_b64 s[8:9], 0x8000
	s_mov_b64 s[10:11], 0x1000
	v_cndmask_b32_e32 v16, v14, v27, vcc
	v_cmp_lt_i32_e32 vcc, v28, v12
	s_movk_i32 s13, 0x1200
	s_mov_b32 s12, 0x3b000000
	v_cndmask_b32_e32 v12, v14, v28, vcc
	s_mov_b32 s14, 0x358637bd
	s_mov_b32 s15, 0x800000
	s_mov_b32 s20, 0xdde0000
	s_mov_b32 s21, 0xdde1000
	s_mov_b64 s[16:17], 0x2000
	s_mov_b64 s[18:19], 0x4800
	s_mov_b64 s[24:25], 0x11de0000
	s_mov_b64 s[26:27], 0x13de0000
	s_mov_b64 s[28:29], 0xdde0000
	s_mov_b64 s[30:31], 0xdde1000
	s_mov_b64 s[32:33], 0x4be0000
	s_mov_b64 s[34:35], 0x4be1000
	s_mov_b64 s[36:37], 0x4be2000
	s_mov_b64 s[38:39], 0x4be3000
	s_mov_b32 s22, s57
	v_ashrrev_i32_e32 v21, 31, v20
	v_lshlrev_b32_e32 v147, 2, v10
	v_lshlrev_b32_e32 v148, 2, v11
	v_lshlrev_b32_e32 v149, 2, v13
	v_lshlrev_b32_e32 v150, 2, v15
	v_lshlrev_b32_e32 v151, 2, v16
	v_lshlrev_b32_e32 v152, 2, v12
	s_mov_b32 s23, s57
	v_readlane_b32 s2, v244, 2
	v_readlane_b32 s6, v244, 6
	v_readlane_b32 s7, v244, 7
	s_waitcnt vmcnt(1)
	v_mov_b32_e32 v27, v4
	v_mov_b32_e32 v29, v2
	s_waitcnt vmcnt(0)
	v_mov_b32_e32 v31, v8
	v_mov_b32_e32 v33, v6
